# P3 v8: v6 + v^T staging packs token pairs with DPP row shifts + v_perm and writes ds_write_b32 (16 instead of 32 LDS writes per step)
# baseline (speedup 1.0000x reference)
; #define LAS __attribute__((address_space(3)))
; __device__ __forceinline__ void gla_scan_item(const Ctx& C, int item, LAS unsigned char* lds, int tid) {
;     const int jx = item >> 3, bh = (item & 7) * 4 + (jx >> 3), sl = jx & 7, b = bh >> 2, h = bh & 3;
;     LAS bf16* Aq = (LAS bf16*)lds;
;     LAS bf16* Bc = (LAS bf16*)(lds + 25600);
;     LAS bf16* Kt = (LAS bf16*)(lds + 38400);
;     const int wave = tid >> 6, lane = tid & 63, l15 = lane & 15, quad = lane >> 4;
;     f32x4 S[2] = {(f32x4){0.f, 0.f, 0.f, 0.f}, (f32x4){0.f, 0.f, 0.f, 0.f}};
;     *(LAS u32x4*)(Bc + (tid >> 4) * 200 + (tid & 15) * 8) = (u32x4){0u, 0u, 0u, 0u};
;     u32x4 rq0A, rq1A, rsA, rk0A, rk1A, rvA = (u32x4){0u, 0u, 0u, 0u}; f32x4 rdA;
;     u32x4 rq0B, rq1B, rsB, rk0B, rk1B, rvB = (u32x4){0u, 0u, 0u, 0u}; f32x4 rdB;
.LBB0_428:
	s_cmp_lt_i32 s96, 4
	s_cselect_b64 s[4:5], -1, 0
	s_add_u32 s6, s94, 0xb300000
	s_addc_u32 s7, s95, 0
	s_and_b64 s[0:1], s[4:5], s[0:1]
	s_andn2_b64 vcc, exec, s[0:1]
	s_cbranch_vccnz .LBB0_496
	s_cmpk_gt_i32 s2, 0xff
	s_cbranch_scc1 .LBB0_496
	v_readfirstlane_b32 s32, v163
	v_and_b32_e32 v203, 63, v162
	v_and_b32_e32 v202, 15, v162
	v_bfe_u32 v201, v162, 4, 2
	v_lshrrev_b32_e32 v200, 4, v203
	v_lshl_add_u32 v200, v163, 3, v200
	v_and_b32_e32 v199, 15, v200
	v_xor_b32_e32 v199, v199, v202
	v_lshlrev_b32_e32 v255, 10, v200
	v_lshl_add_u32 v255, v199, 4, v255
	v_lshrrev_b32_e32 v200, 4, v203
	v_lshl_add_u32 v200, v163, 3, v200
	v_add_u32_e32 v200, 4, v200
	v_and_b32_e32 v199, 15, v200
	v_xor_b32_e32 v199, v199, v202
	v_lshlrev_b32_e32 v254, 10, v200
	v_lshl_add_u32 v254, v199, 4, v254
	v_lshrrev_b32_e32 v200, 3, v203
	v_lshl_add_u32 v200, v163, 3, v200
	v_bfe_u32 v199, v200, 1, 3
	v_and_b32_e32 v198, 7, v203
	v_xor_b32_e32 v199, v199, v198
	v_lshlrev_b32_e32 v253, 7, v200
	v_lshl_add_u32 v253, v199, 4, v253
	v_lshrrev_b32_e32 v200, 3, v203
	v_lshl_add_u32 v200, v163, 4, v200
	v_bfe_u32 v199, v200, 1, 3
	v_and_b32_e32 v198, 7, v203
	v_xor_b32_e32 v199, v199, v198
	v_lshlrev_b32_e32 v252, 7, v200
	v_lshl_add_u32 v252, v199, 4, v252
	v_lshrrev_b32_e32 v200, 3, v203
	v_lshl_add_u32 v200, v163, 4, v200
	v_add_u32_e32 v200, 8, v200
	v_bfe_u32 v199, v200, 1, 3
	v_and_b32_e32 v198, 7, v203
	v_xor_b32_e32 v199, v199, v198
	v_lshlrev_b32_e32 v251, 7, v200
	v_lshl_add_u32 v251, v199, 4, v251
	s_lshl_b32 s46, s32, 11
	s_lshl_b32 s47, s32, 10
	s_add_i32 s47, s47, 0x4000
	s_add_i32 s48, s46, 0x6000
	v_and_b32_e32 v200, 1, v163
	v_lshl_add_u32 v200, v200, 5, v202
	v_or_b32_e32 v199, 0, v201
	v_and_b32_e32 v198, 15, v200
	v_xor_b32_e32 v199, v199, v198
	v_lshlrev_b32_e32 v241, 8, v200
	v_lshl_add_u32 v241, v199, 4, v241
	v_or_b32_e32 v199, 4, v201
	v_and_b32_e32 v198, 15, v200
	v_xor_b32_e32 v199, v199, v198
	v_lshlrev_b32_e32 v240, 8, v200
	v_lshl_add_u32 v240, v199, 4, v240
	v_or_b32_e32 v199, 8, v201
	v_and_b32_e32 v198, 15, v200
	v_xor_b32_e32 v199, v199, v198
	v_lshlrev_b32_e32 v239, 8, v200
	v_lshl_add_u32 v239, v199, 4, v239
	v_or_b32_e32 v199, 12, v201
	v_and_b32_e32 v198, 15, v200
	v_xor_b32_e32 v199, v199, v198
	v_lshlrev_b32_e32 v238, 8, v200
	v_lshl_add_u32 v238, v199, 4, v238
	v_or_b32_e32 v199, 0, v201
	v_bfe_u32 v198, v200, 1, 3
	v_xor_b32_e32 v199, v199, v198
	v_lshlrev_b32_e32 v231, 7, v200
	v_lshl_add_u32 v231, v199, 4, v231
	v_add_u32_e32 v231, 0x4000, v231
	v_or_b32_e32 v199, 4, v201
	v_bfe_u32 v198, v200, 1, 3
	v_xor_b32_e32 v199, v199, v198
	v_lshlrev_b32_e32 v230, 7, v200
	v_lshl_add_u32 v230, v199, 4, v230
	v_add_u32_e32 v230, 0x4000, v230
	v_lshlrev_b32_e32 v248, 11, v200
	v_lshl_add_u32 v248, v201, 3, v248
	v_add_u32_e32 v247, 0x8000, v248
	v_or_b32_e32 v199, 0, v201
	v_and_b32_e32 v198, 15, v202
	v_xor_b32_e32 v199, v199, v198
	v_lshlrev_b32_e32 v223, 8, v202
	v_lshl_add_u32 v223, v199, 4, v223
	v_add_u32_e32 v223, 0x1e000, v223
	v_or_b32_e32 v199, 4, v201
	v_and_b32_e32 v198, 15, v202
	v_xor_b32_e32 v199, v199, v198
	v_lshlrev_b32_e32 v222, 8, v202
	v_lshl_add_u32 v222, v199, 4, v222
	v_add_u32_e32 v222, 0x1e000, v222
	v_or_b32_e32 v199, 8, v201
	v_and_b32_e32 v198, 15, v202
	v_xor_b32_e32 v199, v199, v198
	v_lshlrev_b32_e32 v221, 8, v202
	v_lshl_add_u32 v221, v199, 4, v221
	v_add_u32_e32 v221, 0x1e000, v221
	v_or_b32_e32 v199, 12, v201
	v_and_b32_e32 v198, 15, v202
	v_xor_b32_e32 v199, v199, v198
	v_lshlrev_b32_e32 v220, 8, v202
	v_lshl_add_u32 v220, v199, 4, v220
	v_add_u32_e32 v220, 0x1e000, v220
	v_or_b32_e32 v199, 0, v201
	v_bfe_u32 v198, v202, 1, 3
	v_xor_b32_e32 v199, v199, v198
	v_lshlrev_b32_e32 v219, 7, v202
	v_lshl_add_u32 v219, v199, 4, v219
	v_add_u32_e32 v219, 0x20100, v219
	v_or_b32_e32 v199, 4, v201
	v_bfe_u32 v198, v202, 1, 3
	v_xor_b32_e32 v199, v199, v198
	v_lshlrev_b32_e32 v218, 7, v202
	v_lshl_add_u32 v218, v199, 4, v218
	v_add_u32_e32 v218, 0x20100, v218
	v_and_b32_e32 v200, 1, v163
	v_lshl_add_u32 v200, v200, 6, v202
	v_or_b32_e32 v199, 0, v201
	v_bfe_u32 v198, v200, 1, 3
	v_xor_b32_e32 v199, v199, v198
	v_lshlrev_b32_e32 v227, 7, v200
	v_lshl_add_u32 v227, v199, 4, v227
	v_add_u32_e32 v227, 0x6000, v227
	v_or_b32_e32 v199, 4, v201
	v_bfe_u32 v198, v200, 1, 3
	v_xor_b32_e32 v199, v199, v198
	v_lshlrev_b32_e32 v226, 7, v200
	v_lshl_add_u32 v226, v199, 4, v226
	v_add_u32_e32 v226, 0x6000, v226
	v_or_b32_e32 v199, 0, v201
	v_bfe_u32 v198, v202, 1, 3
	v_xor_b32_e32 v199, v199, v198
	v_lshlrev_b32_e32 v217, 7, v202
	v_lshl_add_u32 v217, v199, 4, v217
	v_add_u32_e32 v217, 0x20100, v217
	v_or_b32_e32 v199, 4, v201
	v_bfe_u32 v198, v202, 1, 3
	v_xor_b32_e32 v199, v199, v198
	v_lshlrev_b32_e32 v216, 7, v202
	v_lshl_add_u32 v216, v199, 4, v216
	v_add_u32_e32 v216, 0x20100, v216
	v_add_u32_e32 v235, 0x14000, v241
	v_add_u32_e32 v234, 0x14000, v240
	v_add_u32_e32 v233, 0x14000, v239
	v_add_u32_e32 v232, 0x14000, v238
	v_add_u32_e32 v229, 0x14000, v231
	v_add_u32_e32 v228, 0x14000, v230
	v_add_u32_e32 v225, 0x14000, v227
	v_add_u32_e32 v224, 0x14000, v226
	v_and_b32_e32 v200, 1, v163
	v_lshrrev_b32_e32 v199, 1, v201
	v_lshl_add_u32 v199, v200, 3, v199
	v_xor_b32_e32 v199, v199, v202
	v_lshlrev_b32_e32 v215, 8, v202
	v_lshl_add_u32 v215, v199, 4, v215
	v_and_b32_e32 v199, 1, v201
	v_lshl_add_u32 v215, v199, 3, v215
	v_add_u32_e32 v215, 0x1e000, v215
	v_and_b32_e32 v200, 1, v163
	v_lshrrev_b32_e32 v199, 1, v201
	v_lshl_add_u32 v199, v200, 3, v199
	v_add_u32_e32 v199, 2, v199
	v_xor_b32_e32 v199, v199, v202
	v_lshlrev_b32_e32 v214, 8, v202
	v_lshl_add_u32 v214, v199, 4, v214
	v_and_b32_e32 v199, 1, v201
	v_lshl_add_u32 v214, v199, 3, v214
	v_add_u32_e32 v214, 0x1e000, v214
	v_and_b32_e32 v200, 1, v163
	v_lshrrev_b32_e32 v199, 1, v201
	v_lshl_add_u32 v199, v200, 3, v199
	v_add_u32_e32 v199, 4, v199
	v_xor_b32_e32 v199, v199, v202
	v_lshlrev_b32_e32 v213, 8, v202
	v_lshl_add_u32 v213, v199, 4, v213
	v_and_b32_e32 v199, 1, v201
	v_lshl_add_u32 v213, v199, 3, v213
	v_add_u32_e32 v213, 0x1e000, v213
	v_and_b32_e32 v200, 1, v163
	v_lshrrev_b32_e32 v199, 1, v201
	v_lshl_add_u32 v199, v200, 3, v199
	v_add_u32_e32 v199, 6, v199
	v_xor_b32_e32 v199, v199, v202
	v_lshlrev_b32_e32 v212, 8, v202
	v_lshl_add_u32 v212, v199, 4, v212
	v_and_b32_e32 v199, 1, v201
	v_lshl_add_u32 v212, v199, 3, v212
	v_add_u32_e32 v212, 0x1e000, v212
	v_bfe_u32 v200, v162, 2, 6
	v_and_b32_e32 v198, 3, v162
	v_lshl_add_u32 v199, v198, 3, 0
	v_lshlrev_b32_e32 v211, 7, v199
	v_bfe_u32 v199, v199, 1, 3
	v_lshrrev_b32_e32 v246, 3, v200
	v_xor_b32_e32 v199, v199, v246
	v_lshl_add_u32 v211, v199, 4, v211
	v_and_b32_e32 v199, 7, v200
	v_lshl_add_u32 v211, v199, 1, v211
	v_add_u32_e32 v211, 0x20100, v211
	v_lshl_add_u32 v199, v198, 3, 1
	v_lshlrev_b32_e32 v210, 7, v199
	v_bfe_u32 v199, v199, 1, 3
	v_lshrrev_b32_e32 v246, 3, v200
	v_xor_b32_e32 v199, v199, v246
	v_lshl_add_u32 v210, v199, 4, v210
	v_and_b32_e32 v199, 7, v200
	v_lshl_add_u32 v210, v199, 1, v210
	v_add_u32_e32 v210, 0x20100, v210
	v_lshl_add_u32 v199, v198, 3, 2
	v_lshlrev_b32_e32 v209, 7, v199
	v_bfe_u32 v199, v199, 1, 3
	v_lshrrev_b32_e32 v246, 3, v200
	v_xor_b32_e32 v199, v199, v246
	v_lshl_add_u32 v209, v199, 4, v209
	v_and_b32_e32 v199, 7, v200
	v_lshl_add_u32 v209, v199, 1, v209
	v_add_u32_e32 v209, 0x20100, v209
	v_lshl_add_u32 v199, v198, 3, 3
	v_lshlrev_b32_e32 v208, 7, v199
	v_bfe_u32 v199, v199, 1, 3
	v_lshrrev_b32_e32 v246, 3, v200
	v_xor_b32_e32 v199, v199, v246
	v_lshl_add_u32 v208, v199, 4, v208
	v_and_b32_e32 v199, 7, v200
	v_lshl_add_u32 v208, v199, 1, v208
	v_add_u32_e32 v208, 0x20100, v208
	v_lshl_add_u32 v199, v198, 3, 4
	v_lshlrev_b32_e32 v207, 7, v199
	v_bfe_u32 v199, v199, 1, 3
	v_lshrrev_b32_e32 v246, 3, v200
	v_xor_b32_e32 v199, v199, v246
	v_lshl_add_u32 v207, v199, 4, v207
	v_and_b32_e32 v199, 7, v200
	v_lshl_add_u32 v207, v199, 1, v207
	v_add_u32_e32 v207, 0x20100, v207
	v_lshl_add_u32 v199, v198, 3, 5
	v_lshlrev_b32_e32 v206, 7, v199
	v_bfe_u32 v199, v199, 1, 3
	v_lshrrev_b32_e32 v246, 3, v200
	v_xor_b32_e32 v199, v199, v246
	v_lshl_add_u32 v206, v199, 4, v206
	v_and_b32_e32 v199, 7, v200
	v_lshl_add_u32 v206, v199, 1, v206
	v_add_u32_e32 v206, 0x20100, v206
	v_lshl_add_u32 v199, v198, 3, 6
	v_lshlrev_b32_e32 v205, 7, v199
	v_bfe_u32 v199, v199, 1, 3
	v_lshrrev_b32_e32 v246, 3, v200
	v_xor_b32_e32 v199, v199, v246
	v_lshl_add_u32 v205, v199, 4, v205
	v_and_b32_e32 v199, 7, v200
	v_lshl_add_u32 v205, v199, 1, v205
	v_add_u32_e32 v205, 0x20100, v205
	v_lshl_add_u32 v199, v198, 3, 7
	v_lshlrev_b32_e32 v204, 7, v199
	v_bfe_u32 v199, v199, 1, 3
	v_lshrrev_b32_e32 v246, 3, v200
	v_xor_b32_e32 v199, v199, v246
	v_lshl_add_u32 v204, v199, 4, v204
	v_and_b32_e32 v199, 7, v200
	v_lshl_add_u32 v204, v199, 1, v204
	v_add_u32_e32 v204, 0x20100, v204
	v_bfe_u32 v200, v162, 2, 6
	v_and_b32_e32 v199, 3, v162
	v_and_b32_e32 v198, 1, v200
	v_lshl_add_u32 v198, v199, 3, v198
	v_lshlrev_b32_e32 v197, 7, v198
	v_bfe_u32 v198, v198, 1, 3
	v_lshrrev_b32_e32 v246, 3, v200
	v_xor_b32_e32 v198, v198, v246
	v_lshl_add_u32 v197, v198, 4, v197
	v_and_b32_e32 v198, 6, v200
	v_lshl_add_u32 v197, v198, 1, v197
	v_add_u32_e32 v197, 0x20100, v197
	v_and_b32_e32 v198, 1, v200
	v_lshl_add_u32 v198, v199, 3, v198
	v_add_u32_e32 v198, 2, v198
	v_lshlrev_b32_e32 v196, 7, v198
	v_bfe_u32 v198, v198, 1, 3
	v_lshrrev_b32_e32 v246, 3, v200
	v_xor_b32_e32 v198, v198, v246
	v_lshl_add_u32 v196, v198, 4, v196
	v_and_b32_e32 v198, 6, v200
	v_lshl_add_u32 v196, v198, 1, v196
	v_add_u32_e32 v196, 0x20100, v196
	v_and_b32_e32 v198, 1, v200
	v_lshl_add_u32 v198, v199, 3, v198
	v_add_u32_e32 v198, 4, v198
	v_lshlrev_b32_e32 v195, 7, v198
	v_bfe_u32 v198, v198, 1, 3
	v_lshrrev_b32_e32 v246, 3, v200
	v_xor_b32_e32 v198, v198, v246
	v_lshl_add_u32 v195, v198, 4, v195
	v_and_b32_e32 v198, 6, v200
	v_lshl_add_u32 v195, v198, 1, v195
	v_add_u32_e32 v195, 0x20100, v195
	v_and_b32_e32 v198, 1, v200
	v_lshl_add_u32 v198, v199, 3, v198
	v_add_u32_e32 v198, 6, v198
	v_lshlrev_b32_e32 v194, 7, v198
	v_bfe_u32 v198, v198, 1, 3
	v_lshrrev_b32_e32 v246, 3, v200
	v_xor_b32_e32 v198, v198, v246
	v_lshl_add_u32 v194, v198, 4, v194
	v_and_b32_e32 v198, 6, v200
	v_lshl_add_u32 v194, v198, 1, v194
	v_add_u32_e32 v194, 0x20100, v194
	v_and_b32_e32 v198, 4, v162
	v_cmp_ne_u32_e32 vcc, 0, v198
	v_mov_b32_e32 v198, 0x05040100
	v_mov_b32_e32 v193, 0x03020706
	v_cndmask_b32_e32 v193, v198, v193, vcc
	v_lshlrev_b32_e32 v250, 14, v200
	v_lshl_add_u32 v250, v199, 4, v250
	v_and_b32_e32 v200, 1, v163
	v_lshlrev_b32_e32 v249, 8, v200
	v_lshl_add_u32 v249, v201, 4, v249
	v_lshlrev_b32_e32 v245, 16, v200
	v_lshl_add_u32 v245, v201, 12, v245
	v_lshl_add_u32 v245, v202, 2, v245
	v_add_u32_e32 v244, 0x4000, v245
	v_add_u32_e32 v243, 0x8000, v245
	v_add_u32_e32 v242, 0xc000, v245
	v_lshlrev_b32_e32 v246, 4, v162
	v_add_u32_e32 v246, 0x1e000, v246
	v_mov_b32_e32 v8, 0
	v_mov_b32_e32 v9, 0
	v_mov_b32_e32 v10, 0
	v_mov_b32_e32 v11, 0
	s_cmp_gt_u32 s32, 3
	s_cbranch_scc1 .Lp3V_entry
	s_cmp_gt_u32 s32, 1
	s_cbranch_scc1 .Lp3S_entry

; #define LAS __attribute__((address_space(3)))
; __device__ __forceinline__ void gla_scan_item(const Ctx& C, int item, LAS unsigned char* lds, int tid) {
;     const int jx = item >> 3, bh = (item & 7) * 4 + (jx >> 3), sl = jx & 7, b = bh >> 2, h = bh & 3;
;     LAS bf16* Aq = (LAS bf16*)lds;
;     LAS bf16* Bc = (LAS bf16*)(lds + 25600);
;     LAS bf16* Kt = (LAS bf16*)(lds + 38400);
;     const int wave = tid >> 6, lane = tid & 63, l15 = lane & 15, quad = lane >> 4;
;     f32x4 S[2] = {(f32x4){0.f, 0.f, 0.f, 0.f}, (f32x4){0.f, 0.f, 0.f, 0.f}};
;     *(LAS u32x4*)(Bc + (tid >> 4) * 200 + (tid & 15) * 8) = (u32x4){0u, 0u, 0u, 0u};
;     u32x4 rq0A, rq1A, rsA, rk0A, rk1A, rvA = (u32x4){0u, 0u, 0u, 0u}; f32x4 rdA;
;     u32x4 rq0B, rq1B, rsB, rk0B, rk1B, rvB = (u32x4){0u, 0u, 0u, 0u}; f32x4 rdB;
.Lp3V_item:
	s_lshr_b32 s4, s3, 3
	s_and_b32 s41, s4, 7
	s_lshr_b32 s5, s4, 3
	s_and_b32 s37, s3, 7
	s_lshl_b32 s37, s37, 2
	s_add_i32 s37, s37, s5
	s_lshr_b32 s39, s37, 2
	s_and_b32 s40, s37, 3
	s_add_u32 s8, s94, 0x1d800000
	s_addc_u32 s9, s95, 0
	s_lshl_b32 s31, s39, 21
	s_add_u32 s8, s8, s31
	s_addc_u32 s9, s9, 0
	s_lshl_b32 s31, s40, 8
	s_add_u32 s8, s8, s31
	s_addc_u32 s9, s9, 0
	s_add_u32 s10, s94, 0x2f00000
	s_addc_u32 s11, s95, 0
	s_lshl_b32 s31, s37, 18
	s_add_u32 s10, s10, s31
	s_addc_u32 s11, s11, 0
	s_add_u32 s12, s94, 0x3700000
	s_addc_u32 s13, s95, 0
	s_lshl_b32 s31, s37, 19
	s_add_u32 s12, s12, s31
	s_addc_u32 s13, s13, 0
	s_add_u32 s14, s94, 0xd402000
	s_addc_u32 s15, s95, 0
	s_lshl_b32 s31, s39, 25
	s_add_u32 s14, s14, s31
	s_addc_u32 s15, s15, 0
	s_lshl_b32 s31, s40, 9
	s_add_u32 s14, s14, s31
	s_addc_u32 s15, s15, 0
	s_lshl_b32 s31, s41, 6
	s_add_u32 s14, s14, s31
	s_addc_u32 s15, s15, 0
	ds_write_b128 v246, v[8:11]
	s_mov_b32 m0, s46
	s_nop 0
	global_load_lds_dwordx4 v255, s[8:9]
	s_add_i32 m0, s46, 0x400
	s_nop 0
	global_load_lds_dwordx4 v254, s[8:9]
	s_mov_b32 m0, s47
	s_nop 0
	global_load_lds_dwordx4 v253, s[10:11]
	s_mov_b32 m0, s48
	s_nop 0
	global_load_lds_dwordx4 v252, s[12:13]
	s_add_i32 m0, s48, 0x400
	s_nop 0
	global_load_lds_dwordx4 v251, s[12:13]
	s_add_u32 s8, s8, 0x10000
	s_addc_u32 s9, s9, 0
	s_add_u32 s10, s10, 0x2000
	s_addc_u32 s11, s11, 0
	s_add_u32 s12, s12, 0x4000
	s_addc_u32 s13, s13, 0
	s_add_i32 m0, s46, 0xa000
	s_nop 0
	global_load_lds_dwordx4 v255, s[8:9]
	s_add_i32 m0, s46, 0xa400
	s_nop 0
	global_load_lds_dwordx4 v254, s[8:9]
	s_add_i32 m0, s47, 0xa000
	s_nop 0
	global_load_lds_dwordx4 v253, s[10:11]
	s_add_i32 m0, s48, 0xa000
	s_nop 0
	global_load_lds_dwordx4 v252, s[12:13]
	s_add_i32 m0, s48, 0xa400
	s_nop 0
	global_load_lds_dwordx4 v251, s[12:13]
	s_add_u32 s8, s8, 0x10000
	s_addc_u32 s9, s9, 0
	s_add_u32 s10, s10, 0x2000
	s_addc_u32 s11, s11, 0
	s_add_u32 s12, s12, 0x4000
	s_addc_u32 s13, s13, 0
	global_load_dwordx4 v[12:15], v250, s[14:15]
	s_add_u32 s14, s14, 0x100000
	s_addc_u32 s15, s15, 0
	global_load_dwordx4 v[16:19], v250, s[14:15]
	s_add_u32 s14, s14, 0x100000
	s_addc_u32 s15, s15, 0
	global_load_dwordx4 v[20:23], v250, s[14:15]
	s_add_u32 s14, s14, 0x100000
	s_addc_u32 s15, s15, 0
	s_waitcnt vmcnt(0)
	v_mov_b32_dpp v192, v12 row_shl:4 row_mask:0xf bank_mask:0x5
	v_mov_b32_dpp v192, v12 row_shr:4 row_mask:0xf bank_mask:0xa
	v_mov_b32_dpp v191, v13 row_shl:4 row_mask:0xf bank_mask:0x5
	v_mov_b32_dpp v191, v13 row_shr:4 row_mask:0xf bank_mask:0xa
	v_mov_b32_dpp v190, v14 row_shl:4 row_mask:0xf bank_mask:0x5
	v_mov_b32_dpp v190, v14 row_shr:4 row_mask:0xf bank_mask:0xa
	v_mov_b32_dpp v189, v15 row_shl:4 row_mask:0xf bank_mask:0x5
	v_mov_b32_dpp v189, v15 row_shr:4 row_mask:0xf bank_mask:0xa
	v_perm_b32 v188, v192, v12, v193
	v_perm_b32 v187, v191, v13, v193
	v_perm_b32 v186, v190, v14, v193
	v_perm_b32 v185, v189, v15, v193
	ds_write_b32 v197, v188 offset:0
	ds_write_b32 v196, v187 offset:0
	ds_write_b32 v195, v186 offset:0
	ds_write_b32 v194, v185 offset:0
	s_mov_b32 s33, 0
	s_waitcnt lgkmcnt(0)
	s_barrier
.Lp3V_loop:
	s_waitcnt vmcnt(6)
	v_mov_b32_dpp v192, v16 row_shl:4 row_mask:0xf bank_mask:0x5
	v_mov_b32_dpp v192, v16 row_shr:4 row_mask:0xf bank_mask:0xa
	v_mov_b32_dpp v191, v17 row_shl:4 row_mask:0xf bank_mask:0x5
	v_mov_b32_dpp v191, v17 row_shr:4 row_mask:0xf bank_mask:0xa
	v_mov_b32_dpp v190, v18 row_shl:4 row_mask:0xf bank_mask:0x5
	v_mov_b32_dpp v190, v18 row_shr:4 row_mask:0xf bank_mask:0xa
	v_mov_b32_dpp v189, v19 row_shl:4 row_mask:0xf bank_mask:0x5
	v_mov_b32_dpp v189, v19 row_shr:4 row_mask:0xf bank_mask:0xa
	v_perm_b32 v188, v192, v16, v193
	v_perm_b32 v187, v191, v17, v193
	v_perm_b32 v186, v190, v18, v193
	v_perm_b32 v185, v189, v19, v193
	ds_write_b32 v197, v188 offset:12288
	ds_write_b32 v196, v187 offset:12288
	ds_write_b32 v195, v186 offset:12288
	ds_write_b32 v194, v185 offset:12288
	s_add_i32 m0, s46, 0x14000
	s_nop 0
	global_load_lds_dwordx4 v255, s[8:9]
	s_add_i32 m0, s46, 0x14400
	s_nop 0
	global_load_lds_dwordx4 v254, s[8:9]
	s_add_i32 m0, s47, 0x14000
	s_nop 0
	global_load_lds_dwordx4 v253, s[10:11]
	s_add_i32 m0, s48, 0x14000
	s_nop 0
	global_load_lds_dwordx4 v252, s[12:13]
	s_add_i32 m0, s48, 0x14400
	s_nop 0
	global_load_lds_dwordx4 v251, s[12:13]
	s_cmp_lt_u32 s33, 29
	s_cselect_b32 s43, 0x10000, 0
	s_add_u32 s8, s8, s43
	s_addc_u32 s9, s9, 0
	s_cmp_lt_u32 s33, 29
	s_cselect_b32 s43, 0x2000, 0
	s_add_u32 s10, s10, s43
	s_addc_u32 s11, s11, 0
	s_cmp_lt_u32 s33, 29
	s_cselect_b32 s43, 0x4000, 0
	s_add_u32 s12, s12, s43
	s_addc_u32 s13, s13, 0
	global_load_dwordx4 v[12:15], v250, s[14:15]
	s_cmp_lt_u32 s33, 28
	s_cselect_b32 s43, 0x100000, 0
	s_add_u32 s14, s14, s43
	s_addc_u32 s15, s15, 0
	s_add_i32 s33, s33, 1
	s_waitcnt vmcnt(7)
	s_waitcnt lgkmcnt(0)
	s_barrier
	s_waitcnt vmcnt(6)
	v_mov_b32_dpp v192, v20 row_shl:4 row_mask:0xf bank_mask:0x5
	v_mov_b32_dpp v192, v20 row_shr:4 row_mask:0xf bank_mask:0xa
	v_mov_b32_dpp v191, v21 row_shl:4 row_mask:0xf bank_mask:0x5
	v_mov_b32_dpp v191, v21 row_shr:4 row_mask:0xf bank_mask:0xa
	v_mov_b32_dpp v190, v22 row_shl:4 row_mask:0xf bank_mask:0x5
	v_mov_b32_dpp v190, v22 row_shr:4 row_mask:0xf bank_mask:0xa
	v_mov_b32_dpp v189, v23 row_shl:4 row_mask:0xf bank_mask:0x5
	v_mov_b32_dpp v189, v23 row_shr:4 row_mask:0xf bank_mask:0xa
	v_perm_b32 v188, v192, v20, v193
	v_perm_b32 v187, v191, v21, v193
	v_perm_b32 v186, v190, v22, v193
	v_perm_b32 v185, v189, v23, v193
	ds_write_b32 v197, v188 offset:0
	ds_write_b32 v196, v187 offset:0
	ds_write_b32 v195, v186 offset:0
	ds_write_b32 v194, v185 offset:0
	s_mov_b32 m0, s46
	s_nop 0
	global_load_lds_dwordx4 v255, s[8:9]
	s_add_i32 m0, s46, 0x400
	s_nop 0
	global_load_lds_dwordx4 v254, s[8:9]
	s_mov_b32 m0, s47
	s_nop 0
	global_load_lds_dwordx4 v253, s[10:11]
	s_mov_b32 m0, s48
	s_nop 0
	global_load_lds_dwordx4 v252, s[12:13]
	s_add_i32 m0, s48, 0x400
	s_nop 0
	global_load_lds_dwordx4 v251, s[12:13]
	s_cmp_lt_u32 s33, 29
	s_cselect_b32 s43, 0x10000, 0
	s_add_u32 s8, s8, s43
	s_addc_u32 s9, s9, 0
	s_cmp_lt_u32 s33, 29
	s_cselect_b32 s43, 0x2000, 0
	s_add_u32 s10, s10, s43
	s_addc_u32 s11, s11, 0
	s_cmp_lt_u32 s33, 29
	s_cselect_b32 s43, 0x4000, 0
	s_add_u32 s12, s12, s43
	s_addc_u32 s13, s13, 0
	global_load_dwordx4 v[16:19], v250, s[14:15]
	s_cmp_lt_u32 s33, 28
	s_cselect_b32 s43, 0x100000, 0
	s_add_u32 s14, s14, s43
	s_addc_u32 s15, s15, 0
	s_add_i32 s33, s33, 1
	s_waitcnt vmcnt(7)
	s_waitcnt lgkmcnt(0)
	s_barrier
	s_waitcnt vmcnt(6)
	v_mov_b32_dpp v192, v12 row_shl:4 row_mask:0xf bank_mask:0x5
	v_mov_b32_dpp v192, v12 row_shr:4 row_mask:0xf bank_mask:0xa
	v_mov_b32_dpp v191, v13 row_shl:4 row_mask:0xf bank_mask:0x5
	v_mov_b32_dpp v191, v13 row_shr:4 row_mask:0xf bank_mask:0xa
	v_mov_b32_dpp v190, v14 row_shl:4 row_mask:0xf bank_mask:0x5
	v_mov_b32_dpp v190, v14 row_shr:4 row_mask:0xf bank_mask:0xa
	v_mov_b32_dpp v189, v15 row_shl:4 row_mask:0xf bank_mask:0x5
	v_mov_b32_dpp v189, v15 row_shr:4 row_mask:0xf bank_mask:0xa
	v_perm_b32 v188, v192, v12, v193
	v_perm_b32 v187, v191, v13, v193
	v_perm_b32 v186, v190, v14, v193
	v_perm_b32 v185, v189, v15, v193
	ds_write_b32 v197, v188 offset:12288
	ds_write_b32 v196, v187 offset:12288
	ds_write_b32 v195, v186 offset:12288
	ds_write_b32 v194, v185 offset:12288
	s_add_i32 m0, s46, 0xa000
	s_nop 0
	global_load_lds_dwordx4 v255, s[8:9]
	s_add_i32 m0, s46, 0xa400
	s_nop 0
	global_load_lds_dwordx4 v254, s[8:9]
	s_add_i32 m0, s47, 0xa000
	s_nop 0
	global_load_lds_dwordx4 v253, s[10:11]
	s_add_i32 m0, s48, 0xa000
	s_nop 0
	global_load_lds_dwordx4 v252, s[12:13]
	s_add_i32 m0, s48, 0xa400
	s_nop 0
	global_load_lds_dwordx4 v251, s[12:13]
	s_cmp_lt_u32 s33, 29
	s_cselect_b32 s43, 0x10000, 0
	s_add_u32 s8, s8, s43
	s_addc_u32 s9, s9, 0
	s_cmp_lt_u32 s33, 29
	s_cselect_b32 s43, 0x2000, 0
	s_add_u32 s10, s10, s43
	s_addc_u32 s11, s11, 0
	s_cmp_lt_u32 s33, 29
	s_cselect_b32 s43, 0x4000, 0
	s_add_u32 s12, s12, s43
	s_addc_u32 s13, s13, 0
	global_load_dwordx4 v[20:23], v250, s[14:15]
	s_cmp_lt_u32 s33, 28
	s_cselect_b32 s43, 0x100000, 0
	s_add_u32 s14, s14, s43
	s_addc_u32 s15, s15, 0
	s_add_i32 s33, s33, 1
	s_waitcnt vmcnt(7)
	s_waitcnt lgkmcnt(0)
	s_barrier
	s_waitcnt vmcnt(6)
	v_mov_b32_dpp v192, v16 row_shl:4 row_mask:0xf bank_mask:0x5
	v_mov_b32_dpp v192, v16 row_shr:4 row_mask:0xf bank_mask:0xa
	v_mov_b32_dpp v191, v17 row_shl:4 row_mask:0xf bank_mask:0x5
	v_mov_b32_dpp v191, v17 row_shr:4 row_mask:0xf bank_mask:0xa
	v_mov_b32_dpp v190, v18 row_shl:4 row_mask:0xf bank_mask:0x5
	v_mov_b32_dpp v190, v18 row_shr:4 row_mask:0xf bank_mask:0xa
	v_mov_b32_dpp v189, v19 row_shl:4 row_mask:0xf bank_mask:0x5
	v_mov_b32_dpp v189, v19 row_shr:4 row_mask:0xf bank_mask:0xa
	v_perm_b32 v188, v192, v16, v193
	v_perm_b32 v187, v191, v17, v193
	v_perm_b32 v186, v190, v18, v193
	v_perm_b32 v185, v189, v19, v193
	ds_write_b32 v197, v188 offset:0
	ds_write_b32 v196, v187 offset:0
	ds_write_b32 v195, v186 offset:0
	ds_write_b32 v194, v185 offset:0
	s_add_i32 m0, s46, 0x14000
	s_nop 0
	global_load_lds_dwordx4 v255, s[8:9]
	s_add_i32 m0, s46, 0x14400
	s_nop 0
	global_load_lds_dwordx4 v254, s[8:9]
	s_add_i32 m0, s47, 0x14000
	s_nop 0
	global_load_lds_dwordx4 v253, s[10:11]
	s_add_i32 m0, s48, 0x14000
	s_nop 0
	global_load_lds_dwordx4 v252, s[12:13]
	s_add_i32 m0, s48, 0x14400
	s_nop 0
	global_load_lds_dwordx4 v251, s[12:13]
	s_cmp_lt_u32 s33, 29
	s_cselect_b32 s43, 0x10000, 0
	s_add_u32 s8, s8, s43
	s_addc_u32 s9, s9, 0
	s_cmp_lt_u32 s33, 29
	s_cselect_b32 s43, 0x2000, 0
	s_add_u32 s10, s10, s43
	s_addc_u32 s11, s11, 0
	s_cmp_lt_u32 s33, 29
	s_cselect_b32 s43, 0x4000, 0
	s_add_u32 s12, s12, s43
	s_addc_u32 s13, s13, 0
	global_load_dwordx4 v[12:15], v250, s[14:15]
	s_cmp_lt_u32 s33, 28
	s_cselect_b32 s43, 0x100000, 0
	s_add_u32 s14, s14, s43
	s_addc_u32 s15, s15, 0
	s_add_i32 s33, s33, 1
	s_waitcnt vmcnt(7)
	s_waitcnt lgkmcnt(0)
	s_barrier
	s_waitcnt vmcnt(6)
	v_mov_b32_dpp v192, v20 row_shl:4 row_mask:0xf bank_mask:0x5
	v_mov_b32_dpp v192, v20 row_shr:4 row_mask:0xf bank_mask:0xa
	v_mov_b32_dpp v191, v21 row_shl:4 row_mask:0xf bank_mask:0x5
	v_mov_b32_dpp v191, v21 row_shr:4 row_mask:0xf bank_mask:0xa
	v_mov_b32_dpp v190, v22 row_shl:4 row_mask:0xf bank_mask:0x5
	v_mov_b32_dpp v190, v22 row_shr:4 row_mask:0xf bank_mask:0xa
	v_mov_b32_dpp v189, v23 row_shl:4 row_mask:0xf bank_mask:0x5
	v_mov_b32_dpp v189, v23 row_shr:4 row_mask:0xf bank_mask:0xa
	v_perm_b32 v188, v192, v20, v193
	v_perm_b32 v187, v191, v21, v193
	v_perm_b32 v186, v190, v22, v193
	v_perm_b32 v185, v189, v23, v193
	ds_write_b32 v197, v188 offset:12288
	ds_write_b32 v196, v187 offset:12288
	ds_write_b32 v195, v186 offset:12288
	ds_write_b32 v194, v185 offset:12288
	s_mov_b32 m0, s46
	s_nop 0
	global_load_lds_dwordx4 v255, s[8:9]
	s_add_i32 m0, s46, 0x400
	s_nop 0
	global_load_lds_dwordx4 v254, s[8:9]
	s_mov_b32 m0, s47
	s_nop 0
	global_load_lds_dwordx4 v253, s[10:11]
	s_mov_b32 m0, s48
	s_nop 0
	global_load_lds_dwordx4 v252, s[12:13]
	s_add_i32 m0, s48, 0x400
	s_nop 0
	global_load_lds_dwordx4 v251, s[12:13]
	s_cmp_lt_u32 s33, 29
	s_cselect_b32 s43, 0x10000, 0
	s_add_u32 s8, s8, s43
	s_addc_u32 s9, s9, 0
	s_cmp_lt_u32 s33, 29
	s_cselect_b32 s43, 0x2000, 0
	s_add_u32 s10, s10, s43
	s_addc_u32 s11, s11, 0
	s_cmp_lt_u32 s33, 29
	s_cselect_b32 s43, 0x4000, 0
	s_add_u32 s12, s12, s43
	s_addc_u32 s13, s13, 0
	global_load_dwordx4 v[16:19], v250, s[14:15]
	s_cmp_lt_u32 s33, 28
	s_cselect_b32 s43, 0x100000, 0
	s_add_u32 s14, s14, s43
	s_addc_u32 s15, s15, 0
	s_add_i32 s33, s33, 1
	s_waitcnt vmcnt(7)
	s_waitcnt lgkmcnt(0)
	s_barrier
	s_waitcnt vmcnt(6)
	v_mov_b32_dpp v192, v12 row_shl:4 row_mask:0xf bank_mask:0x5
	v_mov_b32_dpp v192, v12 row_shr:4 row_mask:0xf bank_mask:0xa
	v_mov_b32_dpp v191, v13 row_shl:4 row_mask:0xf bank_mask:0x5
	v_mov_b32_dpp v191, v13 row_shr:4 row_mask:0xf bank_mask:0xa
	v_mov_b32_dpp v190, v14 row_shl:4 row_mask:0xf bank_mask:0x5
	v_mov_b32_dpp v190, v14 row_shr:4 row_mask:0xf bank_mask:0xa
	v_mov_b32_dpp v189, v15 row_shl:4 row_mask:0xf bank_mask:0x5
	v_mov_b32_dpp v189, v15 row_shr:4 row_mask:0xf bank_mask:0xa
	v_perm_b32 v188, v192, v12, v193
	v_perm_b32 v187, v191, v13, v193
	v_perm_b32 v186, v190, v14, v193
	v_perm_b32 v185, v189, v15, v193
	ds_write_b32 v197, v188 offset:0
	ds_write_b32 v196, v187 offset:0
	ds_write_b32 v195, v186 offset:0
	ds_write_b32 v194, v185 offset:0
	s_add_i32 m0, s46, 0xa000
	s_nop 0
	global_load_lds_dwordx4 v255, s[8:9]
	s_add_i32 m0, s46, 0xa400
	s_nop 0
	global_load_lds_dwordx4 v254, s[8:9]
	s_add_i32 m0, s47, 0xa000
	s_nop 0
	global_load_lds_dwordx4 v253, s[10:11]
	s_add_i32 m0, s48, 0xa000
	s_nop 0
	global_load_lds_dwordx4 v252, s[12:13]
	s_add_i32 m0, s48, 0xa400
	s_nop 0
	global_load_lds_dwordx4 v251, s[12:13]
	s_cmp_lt_u32 s33, 29
	s_cselect_b32 s43, 0x10000, 0
	s_add_u32 s8, s8, s43
	s_addc_u32 s9, s9, 0
	s_cmp_lt_u32 s33, 29
	s_cselect_b32 s43, 0x2000, 0
	s_add_u32 s10, s10, s43
	s_addc_u32 s11, s11, 0
	s_cmp_lt_u32 s33, 29
	s_cselect_b32 s43, 0x4000, 0
	s_add_u32 s12, s12, s43
	s_addc_u32 s13, s13, 0
	global_load_dwordx4 v[20:23], v250, s[14:15]
	s_cmp_lt_u32 s33, 28
	s_cselect_b32 s43, 0x100000, 0
	s_add_u32 s14, s14, s43
	s_addc_u32 s15, s15, 0
	s_add_i32 s33, s33, 1
	s_waitcnt vmcnt(7)
	s_waitcnt lgkmcnt(0)
	s_barrier
	s_cmp_lt_u32 s33, 30
	s_cbranch_scc1 .Lp3V_loop
	s_waitcnt vmcnt(6)
	v_mov_b32_dpp v192, v16 row_shl:4 row_mask:0xf bank_mask:0x5
	v_mov_b32_dpp v192, v16 row_shr:4 row_mask:0xf bank_mask:0xa
	v_mov_b32_dpp v191, v17 row_shl:4 row_mask:0xf bank_mask:0x5
	v_mov_b32_dpp v191, v17 row_shr:4 row_mask:0xf bank_mask:0xa
	v_mov_b32_dpp v190, v18 row_shl:4 row_mask:0xf bank_mask:0x5
	v_mov_b32_dpp v190, v18 row_shr:4 row_mask:0xf bank_mask:0xa
	v_mov_b32_dpp v189, v19 row_shl:4 row_mask:0xf bank_mask:0x5
	v_mov_b32_dpp v189, v19 row_shr:4 row_mask:0xf bank_mask:0xa
	v_perm_b32 v188, v192, v16, v193
	v_perm_b32 v187, v191, v17, v193
	v_perm_b32 v186, v190, v18, v193
	v_perm_b32 v185, v189, v19, v193
	ds_write_b32 v197, v188 offset:12288
	ds_write_b32 v196, v187 offset:12288
	ds_write_b32 v195, v186 offset:12288
	ds_write_b32 v194, v185 offset:12288
	s_add_i32 m0, s46, 0x14000
	s_nop 0
	global_load_lds_dwordx4 v255, s[8:9]
	s_add_i32 m0, s46, 0x14400
	s_nop 0
	global_load_lds_dwordx4 v254, s[8:9]
	s_add_i32 m0, s47, 0x14000
	s_nop 0
	global_load_lds_dwordx4 v253, s[10:11]
	s_add_i32 m0, s48, 0x14000
	s_nop 0
	global_load_lds_dwordx4 v252, s[12:13]
	s_add_i32 m0, s48, 0x14400
	s_nop 0
	global_load_lds_dwordx4 v251, s[12:13]
	s_cmp_lt_u32 s33, 29
	s_cselect_b32 s43, 0x10000, 0
	s_add_u32 s8, s8, s43
	s_addc_u32 s9, s9, 0
	s_cmp_lt_u32 s33, 29
	s_cselect_b32 s43, 0x2000, 0
	s_add_u32 s10, s10, s43
	s_addc_u32 s11, s11, 0
	s_cmp_lt_u32 s33, 29
	s_cselect_b32 s43, 0x4000, 0
	s_add_u32 s12, s12, s43
	s_addc_u32 s13, s13, 0
	global_load_dwordx4 v[12:15], v250, s[14:15]
	s_cmp_lt_u32 s33, 28
	s_cselect_b32 s43, 0x100000, 0
	s_add_u32 s14, s14, s43
	s_addc_u32 s15, s15, 0
	s_add_i32 s33, s33, 1
	s_waitcnt vmcnt(7)
	s_waitcnt lgkmcnt(0)
	s_barrier
	s_waitcnt vmcnt(6)
	v_mov_b32_dpp v192, v20 row_shl:4 row_mask:0xf bank_mask:0x5
	v_mov_b32_dpp v192, v20 row_shr:4 row_mask:0xf bank_mask:0xa
	v_mov_b32_dpp v191, v21 row_shl:4 row_mask:0xf bank_mask:0x5
	v_mov_b32_dpp v191, v21 row_shr:4 row_mask:0xf bank_mask:0xa
	v_mov_b32_dpp v190, v22 row_shl:4 row_mask:0xf bank_mask:0x5
	v_mov_b32_dpp v190, v22 row_shr:4 row_mask:0xf bank_mask:0xa
	v_mov_b32_dpp v189, v23 row_shl:4 row_mask:0xf bank_mask:0x5
	v_mov_b32_dpp v189, v23 row_shr:4 row_mask:0xf bank_mask:0xa
	v_perm_b32 v188, v192, v20, v193
	v_perm_b32 v187, v191, v21, v193
	v_perm_b32 v186, v190, v22, v193
	v_perm_b32 v185, v189, v23, v193
	ds_write_b32 v197, v188 offset:0
	ds_write_b32 v196, v187 offset:0
	ds_write_b32 v195, v186 offset:0
	ds_write_b32 v194, v185 offset:0
	s_mov_b32 m0, s46
	s_nop 0
	global_load_lds_dwordx4 v255, s[8:9]
	s_add_i32 m0, s46, 0x400
	s_nop 0
	global_load_lds_dwordx4 v254, s[8:9]
	s_mov_b32 m0, s47
	s_nop 0
	global_load_lds_dwordx4 v253, s[10:11]
	s_mov_b32 m0, s48
	s_nop 0
	global_load_lds_dwordx4 v252, s[12:13]
	s_add_i32 m0, s48, 0x400
	s_nop 0
	global_load_lds_dwordx4 v251, s[12:13]
	s_cmp_lt_u32 s33, 29
	s_cselect_b32 s43, 0x10000, 0
	s_add_u32 s8, s8, s43
	s_addc_u32 s9, s9, 0
	s_cmp_lt_u32 s33, 29
	s_cselect_b32 s43, 0x2000, 0
	s_add_u32 s10, s10, s43
	s_addc_u32 s11, s11, 0
	s_cmp_lt_u32 s33, 29
	s_cselect_b32 s43, 0x4000, 0
	s_add_u32 s12, s12, s43
	s_addc_u32 s13, s13, 0
	global_load_dwordx4 v[16:19], v250, s[14:15]
	s_cmp_lt_u32 s33, 28
	s_cselect_b32 s43, 0x100000, 0
	s_add_u32 s14, s14, s43
	s_addc_u32 s15, s15, 0
	s_add_i32 s33, s33, 1
	s_waitcnt vmcnt(7)
	s_waitcnt lgkmcnt(0)
	s_barrier
	s_waitcnt vmcnt(0) lgkmcnt(0)
	s_barrier
	s_add_i32 s3, s3, s42
	s_cmpk_lt_i32 s3, 0x100
	s_cbranch_scc1 .Lp3V_item
	s_branch .Lp3_done
